# FF1 K-loop: LDS-DMA issued in SGPR-base + 32-bit VGPR-offset form, removing the 64-bit VALU address adds
# baseline (speedup 1.0000x reference)
.LBB0_211:
	s_add_i32 s73, s58, 2
	s_add_u32 s74, s56, 0x80
	s_addc_u32 s59, s57, 0
	s_add_i32 s78, 0, 0x10000
	s_cmp_eq_u32 s63, s58
	s_cselect_b32 s59, s51, s59
	s_cselect_b32 s58, s55, s74
	v_add_u32_e32 v0, s78, v146
	s_cselect_b32 s75, s45, s72
	s_cselect_b32 s74, s44, s67
	s_add_i32 s80, 0, 0x14000
	ds_read_b128 v[148:151], v0
	ds_read_b128 v[152:155], v0 offset:1024
	ds_read_b128 v[156:159], v0 offset:2048
	ds_read_b128 v[160:163], v0 offset:3072
	v_add_u32_e32 v0, s80, v146
	ds_read_b128 v[164:167], v0
	ds_read_b128 v[168:171], v0 offset:1024
	ds_read_b128 v[172:175], v0 offset:2048
	ds_read_b128 v[176:179], v0 offset:3072
	s_mov_b32 m0, s31
	s_nop 0
	global_load_lds_dwordx4 v136, s[56:57]
	s_mov_b32 m0, s53
	s_nop 0
	global_load_lds_dwordx4 v132, s[56:57]
	s_add_i32 m0, s27, 0xc000
	s_nop 0
	global_load_lds_dwordx4 v138, s[56:57]
	s_add_i32 m0, s27, 0xe000
	s_nop 0
	global_load_lds_dwordx4 v140, s[56:57]
	ds_read_b128 v[180:183], v147
	ds_read_b128 v[184:187], v147 offset:1024
	ds_read_b128 v[200:203], v147 offset:2048
	ds_read_b128 v[204:207], v147 offset:3072
	ds_read_b128 v[208:211], v147 offset:4096
	ds_read_b128 v[212:215], v147 offset:5120
	ds_read_b128 v[216:219], v147 offset:6144
	ds_read_b128 v[220:223], v147 offset:7168
	s_waitcnt vmcnt(8)
	s_waitcnt lgkmcnt(0)
	s_barrier
	s_setprio 1
	s_waitcnt lgkmcnt(0)
	v_mfma_f32_16x16x32_bf16 v[122:125], v[148:151], v[180:183], v[122:125]
	v_mfma_f32_16x16x32_bf16 v[126:129], v[156:159], v[180:183], v[126:129]
	v_mfma_f32_16x16x32_bf16 v[110:113], v[148:151], v[200:203], v[110:113]
	v_mfma_f32_16x16x32_bf16 v[106:109], v[156:159], v[200:203], v[106:109]
	v_mfma_f32_16x16x32_bf16 v[94:97], v[148:151], v[208:211], v[94:97]
	v_mfma_f32_16x16x32_bf16 v[90:93], v[156:159], v[208:211], v[90:93]
	v_mfma_f32_16x16x32_bf16 v[78:81], v[148:151], v[216:219], v[78:81]
	v_mfma_f32_16x16x32_bf16 v[74:77], v[156:159], v[216:219], v[74:77]
	v_mfma_f32_16x16x32_bf16 v[122:125], v[152:155], v[184:187], v[122:125]
	v_mfma_f32_16x16x32_bf16 v[126:129], v[160:163], v[184:187], v[126:129]
	v_mfma_f32_16x16x32_bf16 v[110:113], v[152:155], v[204:207], v[110:113]
	v_mfma_f32_16x16x32_bf16 v[106:109], v[160:163], v[204:207], v[106:109]
	v_mfma_f32_16x16x32_bf16 v[94:97], v[152:155], v[212:215], v[94:97]
	v_mfma_f32_16x16x32_bf16 v[90:93], v[160:163], v[212:215], v[90:93]
	v_mfma_f32_16x16x32_bf16 v[78:81], v[152:155], v[220:223], v[78:81]
	v_mfma_f32_16x16x32_bf16 v[74:77], v[160:163], v[220:223], v[74:77]
	s_setprio 0
	s_setprio 1
	v_mfma_f32_16x16x32_bf16 v[118:121], v[164:167], v[180:183], v[118:121]
	v_mfma_f32_16x16x32_bf16 v[114:117], v[172:175], v[180:183], v[114:117]
	v_mfma_f32_16x16x32_bf16 v[102:105], v[164:167], v[200:203], v[102:105]
	v_mfma_f32_16x16x32_bf16 v[98:101], v[172:175], v[200:203], v[98:101]
	v_mfma_f32_16x16x32_bf16 v[86:89], v[164:167], v[208:211], v[86:89]
	v_mfma_f32_16x16x32_bf16 v[82:85], v[172:175], v[208:211], v[82:85]
	v_mfma_f32_16x16x32_bf16 v[70:73], v[164:167], v[216:219], v[70:73]
	v_mfma_f32_16x16x32_bf16 v[66:69], v[172:175], v[216:219], v[66:69]
	v_mfma_f32_16x16x32_bf16 v[118:121], v[168:171], v[184:187], v[118:121]
	v_mfma_f32_16x16x32_bf16 v[114:117], v[176:179], v[184:187], v[114:117]
	v_mfma_f32_16x16x32_bf16 v[102:105], v[168:171], v[204:207], v[102:105]
	v_mfma_f32_16x16x32_bf16 v[98:101], v[176:179], v[204:207], v[98:101]
	v_mfma_f32_16x16x32_bf16 v[86:89], v[168:171], v[212:215], v[86:89]
	v_mfma_f32_16x16x32_bf16 v[82:85], v[176:179], v[212:215], v[82:85]
	v_mfma_f32_16x16x32_bf16 v[70:73], v[168:171], v[220:223], v[70:73]
	v_mfma_f32_16x16x32_bf16 v[66:69], v[176:179], v[220:223], v[66:69]
	s_setprio 0
	s_barrier
	s_add_i32 s78, s78, s5
	s_mov_b32 m0, s78
	ds_read_b128 v[180:183], v147 offset:16384
	ds_read_b128 v[184:187], v147 offset:17408
	ds_read_b128 v[200:203], v147 offset:18432
	ds_read_b128 v[204:207], v147 offset:19456
	ds_read_b128 v[208:211], v147 offset:20480
	ds_read_b128 v[212:215], v147 offset:21504
	ds_read_b128 v[216:219], v147 offset:22528
	ds_read_b128 v[220:223], v147 offset:23552
	global_load_lds_dwordx4 v134, s[74:75]
	s_add_i32 m0, s78, 0x2000
	s_add_u32 s98, s74, 0x80
	s_addc_u32 s99, s75, 0
	global_load_lds_dwordx4 v130, s[74:75]
	s_add_u32 s74, s74, s6
	s_addc_u32 s75, s75, s7
	s_add_i32 s78, s80, s5
	s_mov_b32 m0, s78
	s_add_u32 s100, s74, 0x80
	s_addc_u32 s101, s75, 0
	global_load_lds_dwordx4 v134, s[74:75]
	s_add_i32 m0, s78, 0x2000
	s_nop 0
	global_load_lds_dwordx4 v130, s[74:75]
	s_waitcnt vmcnt(6)
	s_waitcnt lgkmcnt(0)
	s_barrier
	s_setprio 1
	s_waitcnt lgkmcnt(0)
	v_mfma_f32_16x16x32_bf16 v[62:65], v[148:151], v[180:183], v[62:65]
	v_mfma_f32_16x16x32_bf16 v[58:61], v[156:159], v[180:183], v[58:61]
	v_mfma_f32_16x16x32_bf16 v[46:49], v[148:151], v[200:203], v[46:49]
	v_mfma_f32_16x16x32_bf16 v[42:45], v[156:159], v[200:203], v[42:45]
	v_mfma_f32_16x16x32_bf16 v[30:33], v[148:151], v[208:211], v[30:33]
	v_mfma_f32_16x16x32_bf16 v[26:29], v[156:159], v[208:211], v[26:29]
	v_mfma_f32_16x16x32_bf16 v[14:17], v[148:151], v[216:219], v[14:17]
	v_mfma_f32_16x16x32_bf16 v[10:13], v[156:159], v[216:219], v[10:13]
	v_mfma_f32_16x16x32_bf16 v[62:65], v[152:155], v[184:187], v[62:65]
	v_mfma_f32_16x16x32_bf16 v[58:61], v[160:163], v[184:187], v[58:61]
	v_mfma_f32_16x16x32_bf16 v[46:49], v[152:155], v[204:207], v[46:49]
	v_mfma_f32_16x16x32_bf16 v[42:45], v[160:163], v[204:207], v[42:45]
	v_mfma_f32_16x16x32_bf16 v[30:33], v[152:155], v[212:215], v[30:33]
	v_mfma_f32_16x16x32_bf16 v[26:29], v[160:163], v[212:215], v[26:29]
	v_mfma_f32_16x16x32_bf16 v[14:17], v[152:155], v[220:223], v[14:17]
	v_mfma_f32_16x16x32_bf16 v[10:13], v[160:163], v[220:223], v[10:13]
	s_setprio 0
	s_setprio 1
	v_mfma_f32_16x16x32_bf16 v[54:57], v[164:167], v[180:183], v[54:57]
	v_mfma_f32_16x16x32_bf16 v[50:53], v[172:175], v[180:183], v[50:53]
	v_mfma_f32_16x16x32_bf16 v[38:41], v[164:167], v[200:203], v[38:41]
	v_mfma_f32_16x16x32_bf16 v[34:37], v[172:175], v[200:203], v[34:37]
	v_mfma_f32_16x16x32_bf16 v[22:25], v[164:167], v[208:211], v[22:25]
	v_mfma_f32_16x16x32_bf16 v[18:21], v[172:175], v[208:211], v[18:21]
	v_mfma_f32_16x16x32_bf16 v[6:9], v[164:167], v[216:219], v[6:9]
	v_mfma_f32_16x16x32_bf16 v[2:5], v[172:175], v[216:219], v[2:5]
	v_mfma_f32_16x16x32_bf16 v[54:57], v[168:171], v[184:187], v[54:57]
	v_mfma_f32_16x16x32_bf16 v[50:53], v[176:179], v[184:187], v[50:53]
	v_mfma_f32_16x16x32_bf16 v[38:41], v[168:171], v[204:207], v[38:41]
	v_mfma_f32_16x16x32_bf16 v[34:37], v[176:179], v[204:207], v[34:37]
	v_mfma_f32_16x16x32_bf16 v[22:25], v[168:171], v[212:215], v[22:25]
	v_mfma_f32_16x16x32_bf16 v[18:21], v[176:179], v[212:215], v[18:21]
	v_mfma_f32_16x16x32_bf16 v[6:9], v[168:171], v[220:223], v[6:9]
	v_mfma_f32_16x16x32_bf16 v[2:5], v[176:179], v[220:223], v[2:5]
	s_setprio 0
	s_barrier
	s_add_i32 s74, 0, 0x18000
	v_add_u32_e32 v0, s74, v146
	s_add_i32 s75, 0, 0x1c000
	ds_read_b128 v[148:151], v0
	ds_read_b128 v[152:155], v0 offset:1024
	ds_read_b128 v[156:159], v0 offset:2048
	ds_read_b128 v[160:163], v0 offset:3072
	v_add_u32_e32 v0, s75, v146
	ds_read_b128 v[164:167], v0
	ds_read_b128 v[168:171], v0 offset:1024
	ds_read_b128 v[172:175], v0 offset:2048
	ds_read_b128 v[176:179], v0 offset:3072
	s_mov_b32 m0, s27
	s_nop 0
	global_load_lds_dwordx4 v136, s[58:59]
	s_mov_b32 m0, s28
	s_nop 0
	global_load_lds_dwordx4 v132, s[58:59]
	s_add_u32 s58, s58, s2
	s_addc_u32 s59, s59, s3
	s_mov_b32 m0, s29
	s_nop 0
	global_load_lds_dwordx4 v136, s[58:59]
	s_mov_b32 m0, s30
	s_nop 0
	global_load_lds_dwordx4 v132, s[58:59]
	ds_read_b128 v[180:183], v147 offset:32768
	ds_read_b128 v[184:187], v147 offset:33792
	ds_read_b128 v[200:203], v147 offset:34816
	ds_read_b128 v[204:207], v147 offset:35840
	ds_read_b128 v[208:211], v147 offset:36864
	ds_read_b128 v[212:215], v147 offset:37888
	ds_read_b128 v[216:219], v147 offset:38912
	ds_read_b128 v[220:223], v147 offset:39936
	s_waitcnt vmcnt(8)
	s_waitcnt lgkmcnt(0)
	s_barrier
	s_setprio 1
	s_waitcnt lgkmcnt(0)
	v_mfma_f32_16x16x32_bf16 v[122:125], v[148:151], v[180:183], v[122:125]
	v_mfma_f32_16x16x32_bf16 v[126:129], v[156:159], v[180:183], v[126:129]
	v_mfma_f32_16x16x32_bf16 v[110:113], v[148:151], v[200:203], v[110:113]
	v_mfma_f32_16x16x32_bf16 v[106:109], v[156:159], v[200:203], v[106:109]
	v_mfma_f32_16x16x32_bf16 v[94:97], v[148:151], v[208:211], v[94:97]
	v_mfma_f32_16x16x32_bf16 v[90:93], v[156:159], v[208:211], v[90:93]
	v_mfma_f32_16x16x32_bf16 v[78:81], v[148:151], v[216:219], v[78:81]
	v_mfma_f32_16x16x32_bf16 v[74:77], v[156:159], v[216:219], v[74:77]
	v_mfma_f32_16x16x32_bf16 v[122:125], v[152:155], v[184:187], v[122:125]
	v_mfma_f32_16x16x32_bf16 v[126:129], v[160:163], v[184:187], v[126:129]
	v_mfma_f32_16x16x32_bf16 v[110:113], v[152:155], v[204:207], v[110:113]
	v_mfma_f32_16x16x32_bf16 v[106:109], v[160:163], v[204:207], v[106:109]
	v_mfma_f32_16x16x32_bf16 v[94:97], v[152:155], v[212:215], v[94:97]
	v_mfma_f32_16x16x32_bf16 v[90:93], v[160:163], v[212:215], v[90:93]
	v_mfma_f32_16x16x32_bf16 v[78:81], v[152:155], v[220:223], v[78:81]
	v_mfma_f32_16x16x32_bf16 v[74:77], v[160:163], v[220:223], v[74:77]
	s_setprio 0
	s_setprio 1
	v_mfma_f32_16x16x32_bf16 v[118:121], v[164:167], v[180:183], v[118:121]
	v_mfma_f32_16x16x32_bf16 v[114:117], v[172:175], v[180:183], v[114:117]
	v_mfma_f32_16x16x32_bf16 v[102:105], v[164:167], v[200:203], v[102:105]
	v_mfma_f32_16x16x32_bf16 v[98:101], v[172:175], v[200:203], v[98:101]
	v_mfma_f32_16x16x32_bf16 v[86:89], v[164:167], v[208:211], v[86:89]
	v_mfma_f32_16x16x32_bf16 v[82:85], v[172:175], v[208:211], v[82:85]
	v_mfma_f32_16x16x32_bf16 v[70:73], v[164:167], v[216:219], v[70:73]
	v_mfma_f32_16x16x32_bf16 v[66:69], v[172:175], v[216:219], v[66:69]
	v_mfma_f32_16x16x32_bf16 v[118:121], v[168:171], v[184:187], v[118:121]
	v_mfma_f32_16x16x32_bf16 v[114:117], v[176:179], v[184:187], v[114:117]
	v_mfma_f32_16x16x32_bf16 v[102:105], v[168:171], v[204:207], v[102:105]
	v_mfma_f32_16x16x32_bf16 v[98:101], v[176:179], v[204:207], v[98:101]
	v_mfma_f32_16x16x32_bf16 v[86:89], v[168:171], v[212:215], v[86:89]
	v_mfma_f32_16x16x32_bf16 v[82:85], v[176:179], v[212:215], v[82:85]
	v_mfma_f32_16x16x32_bf16 v[70:73], v[168:171], v[220:223], v[70:73]
	v_mfma_f32_16x16x32_bf16 v[66:69], v[176:179], v[220:223], v[66:69]
	s_setprio 0
	s_barrier
	s_add_i32 s58, s74, s5
	s_mov_b32 m0, s58
	ds_read_b128 v[180:183], v147 offset:49152
	ds_read_b128 v[184:187], v147 offset:50176
	ds_read_b128 v[200:203], v147 offset:51200
	ds_read_b128 v[204:207], v147 offset:52224
	ds_read_b128 v[208:211], v147 offset:53248
	ds_read_b128 v[212:215], v147 offset:54272
	ds_read_b128 v[216:219], v147 offset:55296
	ds_read_b128 v[220:223], v147 offset:56320
	global_load_lds_dwordx4 v134, s[98:99]
	s_add_i32 m0, s58, 0x2000
	s_add_i32 s58, s75, s5
	global_load_lds_dwordx4 v130, s[98:99]
	s_mov_b32 m0, s58
	s_nop 0
	global_load_lds_dwordx4 v134, s[100:101]
	s_add_i32 m0, s58, 0x2000
	s_nop 0
	global_load_lds_dwordx4 v130, s[100:101]
	s_waitcnt vmcnt(6)
	s_waitcnt lgkmcnt(0)
	s_barrier
	s_setprio 1
	s_waitcnt lgkmcnt(0)
	v_mfma_f32_16x16x32_bf16 v[62:65], v[148:151], v[180:183], v[62:65]
	v_mfma_f32_16x16x32_bf16 v[58:61], v[156:159], v[180:183], v[58:61]
	v_mfma_f32_16x16x32_bf16 v[46:49], v[148:151], v[200:203], v[46:49]
	v_mfma_f32_16x16x32_bf16 v[42:45], v[156:159], v[200:203], v[42:45]
	v_mfma_f32_16x16x32_bf16 v[30:33], v[148:151], v[208:211], v[30:33]
	v_mfma_f32_16x16x32_bf16 v[26:29], v[156:159], v[208:211], v[26:29]
	v_mfma_f32_16x16x32_bf16 v[14:17], v[148:151], v[216:219], v[14:17]
	v_mfma_f32_16x16x32_bf16 v[10:13], v[156:159], v[216:219], v[10:13]
	v_mfma_f32_16x16x32_bf16 v[62:65], v[152:155], v[184:187], v[62:65]
	v_mfma_f32_16x16x32_bf16 v[58:61], v[160:163], v[184:187], v[58:61]
	v_mfma_f32_16x16x32_bf16 v[46:49], v[152:155], v[204:207], v[46:49]
	v_mfma_f32_16x16x32_bf16 v[42:45], v[160:163], v[204:207], v[42:45]
	v_mfma_f32_16x16x32_bf16 v[30:33], v[152:155], v[212:215], v[30:33]
	v_mfma_f32_16x16x32_bf16 v[26:29], v[160:163], v[212:215], v[26:29]
	v_mfma_f32_16x16x32_bf16 v[14:17], v[152:155], v[220:223], v[14:17]
	v_mfma_f32_16x16x32_bf16 v[10:13], v[160:163], v[220:223], v[10:13]
	s_setprio 0
	s_setprio 1
	v_mfma_f32_16x16x32_bf16 v[54:57], v[164:167], v[180:183], v[54:57]
	v_mfma_f32_16x16x32_bf16 v[50:53], v[172:175], v[180:183], v[50:53]
	v_mfma_f32_16x16x32_bf16 v[38:41], v[164:167], v[200:203], v[38:41]
	v_mfma_f32_16x16x32_bf16 v[34:37], v[172:175], v[200:203], v[34:37]
	v_mfma_f32_16x16x32_bf16 v[22:25], v[164:167], v[208:211], v[22:25]
	v_mfma_f32_16x16x32_bf16 v[18:21], v[172:175], v[208:211], v[18:21]
	v_mfma_f32_16x16x32_bf16 v[6:9], v[164:167], v[216:219], v[6:9]
	v_mfma_f32_16x16x32_bf16 v[2:5], v[172:175], v[216:219], v[2:5]
	v_mfma_f32_16x16x32_bf16 v[54:57], v[168:171], v[184:187], v[54:57]
	v_mfma_f32_16x16x32_bf16 v[50:53], v[176:179], v[184:187], v[50:53]
	v_mfma_f32_16x16x32_bf16 v[38:41], v[168:171], v[204:207], v[38:41]
	v_mfma_f32_16x16x32_bf16 v[34:37], v[176:179], v[204:207], v[34:37]
	v_mfma_f32_16x16x32_bf16 v[22:25], v[168:171], v[212:215], v[22:25]
	v_mfma_f32_16x16x32_bf16 v[18:21], v[176:179], v[212:215], v[18:21]
	v_mfma_f32_16x16x32_bf16 v[6:9], v[168:171], v[220:223], v[6:9]
	v_mfma_f32_16x16x32_bf16 v[2:5], v[176:179], v[220:223], v[2:5]
	s_setprio 0
	s_barrier
	s_add_u32 s56, s56, 0x100
	s_addc_u32 s57, s57, 0
	s_add_u32 s67, s67, 0x100
	s_addc_u32 s72, s72, 0
	s_cmp_ge_i32 s73, s60
	s_mov_b32 s58, s73
	s_cbranch_scc0 .LBB0_211
	v_readlane_b32 s74, v236, 30
	v_readlane_b32 s75, v236, 31
	v_readlane_b32 s73, v236, 32
	s_mov_b32 s78, s76

	.amdhsa_kernel _Z10fwd_kernel4Args
		.amdhsa_group_segment_fixed_size 0
		.amdhsa_private_segment_fixed_size 0
		.amdhsa_kernarg_size 400
		.amdhsa_user_sgpr_count 2
		.amdhsa_user_sgpr_dispatch_ptr 0
		.amdhsa_user_sgpr_queue_ptr 0
		.amdhsa_user_sgpr_kernarg_segment_ptr 1
		.amdhsa_user_sgpr_dispatch_id 0
		.amdhsa_user_sgpr_kernarg_preload_length 0
		.amdhsa_user_sgpr_kernarg_preload_offset 0
		.amdhsa_user_sgpr_private_segment_size 0
		.amdhsa_uses_dynamic_stack 0
		.amdhsa_enable_private_segment 0
		.amdhsa_system_sgpr_workgroup_id_x 1
		.amdhsa_system_sgpr_workgroup_id_y 0
		.amdhsa_system_sgpr_workgroup_id_z 0
		.amdhsa_system_sgpr_workgroup_info 0
		.amdhsa_system_vgpr_workitem_id 2
		.amdhsa_next_free_vgpr 238
		.amdhsa_next_free_sgpr 102
		.amdhsa_accum_offset 240
		.amdhsa_reserve_vcc 1
		.amdhsa_float_round_mode_32 0
		.amdhsa_float_round_mode_16_64 0
		.amdhsa_float_denorm_mode_32 3
		.amdhsa_float_denorm_mode_16_64 3
		.amdhsa_dx10_clamp 1
		.amdhsa_ieee_mode 1
		.amdhsa_fp16_overflow 0
		.amdhsa_tg_split 0
		.amdhsa_exception_fp_ieee_invalid_op 0
		.amdhsa_exception_fp_denorm_src 0
		.amdhsa_exception_fp_ieee_div_zero 0
		.amdhsa_exception_fp_ieee_overflow 0
		.amdhsa_exception_fp_ieee_underflow 0
		.amdhsa_exception_fp_ieee_inexact 0
		.amdhsa_exception_int_div_zero 0
	.end_amdhsa_kernel

amdhsa.kernels:
  - .agpr_count:     0
    .args:
      - .offset:         0
        .size:           144
        .value_kind:     by_value
      - .offset:         144
        .size:           4
        .value_kind:     hidden_block_count_x
      - .offset:         148
        .size:           4
        .value_kind:     hidden_block_count_y
      - .offset:         152
        .size:           4
        .value_kind:     hidden_block_count_z
      - .offset:         156
        .size:           2
        .value_kind:     hidden_group_size_x
      - .offset:         158
        .size:           2
        .value_kind:     hidden_group_size_y
      - .offset:         160
        .size:           2
        .value_kind:     hidden_group_size_z
      - .offset:         162
        .size:           2
        .value_kind:     hidden_remainder_x
      - .offset:         164
        .size:           2
        .value_kind:     hidden_remainder_y
      - .offset:         166
        .size:           2
        .value_kind:     hidden_remainder_z
      - .offset:         184
        .size:           8
        .value_kind:     hidden_global_offset_x
      - .offset:         192
        .size:           8
        .value_kind:     hidden_global_offset_y
      - .offset:         200
        .size:           8
        .value_kind:     hidden_global_offset_z
      - .offset:         208
        .size:           2
        .value_kind:     hidden_grid_dims
      - .offset:         232
        .size:           8
        .value_kind:     hidden_multigrid_sync_arg
      - .offset:         264
        .size:           4
        .value_kind:     hidden_dynamic_lds_size
    .group_segment_fixed_size: 0
    .kernarg_segment_align: 8
    .kernarg_segment_size: 400
    .language:       OpenCL C
    .language_version:
      - 2
      - 0
    .max_flat_workgroup_size: 512
    .name:           _Z10fwd_kernel4Args
    .private_segment_fixed_size: 0
    .sgpr_count:     108
    .sgpr_spill_count: 216
    .symbol:         _Z10fwd_kernel4Args.kd
    .uniform_work_group_size: 1
    .uses_dynamic_stack: false
    .vgpr_count:     238
    .vgpr_spill_count: 0
    .wavefront_size: 64
